# P6 conversion role: bf16 weight stores with default cache policy instead of nt (write-back through L2/MALL); on v48
# baseline (speedup 1.0000x reference)
; #define GAS __attribute__((address_space(1)))
; #define LAS __attribute__((address_space(3)))
; #define LDS_WAIT() asm volatile("s_waitcnt lgkmcnt(0)" ::: "memory")
; __device__ __forceinline__ unsigned pk2(float lo, float hi) { pkf32x2 v = {lo, hi}; pkbf16x2 b = __builtin_convertvector(v, pkbf16x2); return __builtin_bit_cast(unsigned, b); }
; template <bool NT> __device__ __forceinline__ void tr_store(const f32x4 (&v)[16], const TrItem& it, LAS float* scr, int lane) {
;     const int kq = lane >> 4, g = lane & 15;
; #pragma unroll
;     for (int i = 0; i < 16; ++i) { LAS float* d = scr + (4 * i + kq) * 65 + 4 * g; d[0] = v[i].x; d[1] = v[i].y; d[2] = v[i].z; d[3] = v[i].w; }
;     LDS_WAIT(); asm volatile("" ::: "memory");
;     const int c = lane >> 3, rr = lane & 7;
; #pragma unroll
;     for (int j = 0; j < 8; ++j) { const int n = 8 * j + rr; const LAS float* s = scr + (8 * c) * 65 + n;
;         v4u o; o.x = pk2(s[0 * 65], s[1 * 65]); o.y = pk2(s[2 * 65], s[3 * 65]); o.z = pk2(s[4 * 65], s[5 * 65]); o.w = pk2(s[6 * 65], s[7 * 65]);
;         GAS v4u* q = (GAS v4u*)(it.dst + (size_t)n * it.K + 8 * c); if (NT) __builtin_nontemporal_store(o, q); else *q = o; }
;     LDS_WAIT(); asm volatile("" ::: "memory");
; }
.LBB0_1288:
	ds_write2_b32 v172, v58, v59 offset1:1
	ds_write2_b32 v172, v60, v61 offset0:2 offset1:3
	ds_write2_b32 v174, v54, v55 offset1:1
	ds_write2_b32 v175, v56, v57 offset1:1
	ds_write2_b32 v176, v70, v71 offset1:1
	ds_write2_b32 v177, v72, v73 offset1:1
	ds_write2_b32 v178, v66, v67 offset1:1
	ds_write2_b32 v179, v68, v69 offset1:1
	ds_write2_b32 v180, v82, v83 offset1:1
	ds_write2_b32 v181, v84, v85 offset1:1
	ds_write2_b32 v182, v78, v79 offset1:1
	ds_write2_b32 v183, v80, v81 offset1:1
	ds_write2_b32 v184, v98, v99 offset1:1
	ds_write2_b32 v185, v100, v101 offset1:1
	ds_write2_b32 v186, v94, v95 offset1:1
	ds_write2_b32 v187, v96, v97 offset1:1
	ds_write2_b32 v188, v106, v107 offset1:1
	ds_write2_b32 v189, v108, v109 offset1:1
	ds_write2_b32 v190, v102, v103 offset1:1
	ds_write2_b32 v191, v104, v105 offset1:1
	ds_write2_b32 v192, v114, v115 offset1:1
	ds_write2_b32 v193, v116, v117 offset1:1
	ds_write2_b32 v194, v110, v111 offset1:1
	ds_write2_b32 v195, v112, v113 offset1:1
	ds_write2_b32 v196, v122, v123 offset1:1
	ds_write2_b32 v197, v124, v125 offset1:1
	ds_write2_b32 v198, v118, v119 offset1:1
	ds_write2_b32 v199, v120, v121 offset1:1
	ds_write2_b32 v200, v130, v131 offset1:1
	ds_write2_b32 v201, v132, v133 offset1:1
	ds_write2_b32 v202, v126, v127 offset1:1
	ds_write2_b32 v203, v128, v129 offset1:1
	s_waitcnt lgkmcnt(0)
	ds_read2_b32 v[4:5], v169 offset0:65 offset1:73
	ds_read2_b32 v[174:175], v169 offset1:8
	ds_read2_b32 v[176:177], v169 offset0:130 offset1:138
	ds_read2_b32 v[178:179], v169 offset0:195 offset1:203
	ds_read2_b32 v[180:181], v173 offset0:4 offset1:12
	ds_read2_b32 v[182:183], v173 offset0:69 offset1:77
	ds_read2_b32 v[184:185], v173 offset0:134 offset1:142
	ds_read2_b32 v[186:187], v173 offset0:199 offset1:207
	v_mov_b32_e32 v159, v2
	v_lshl_add_u64 v[188:189], v[156:157], 0, v[158:159]
	v_mad_u64_u32 v[190:191], s[8:9], s28, v136, 0
	s_waitcnt lgkmcnt(6)
	v_cvt_pk_bf16_f32 v158, v174, v4
	s_waitcnt lgkmcnt(4)
	v_cvt_pk_bf16_f32 v159, v176, v178
	s_waitcnt lgkmcnt(2)
	v_cvt_pk_bf16_f32 v160, v180, v182
	s_waitcnt lgkmcnt(0)
	v_cvt_pk_bf16_f32 v161, v184, v186
	v_lshl_add_u64 v[190:191], v[190:191], 1, v[188:189]
	global_store_dwordx4 v[190:191], v[158:161], off
	s_mov_b32 s27, s29
	s_nop 0
	v_cvt_pk_bf16_f32 v158, v175, v5
	v_cvt_pk_bf16_f32 v159, v177, v179
	v_cvt_pk_bf16_f32 v160, v181, v183
	v_cvt_pk_bf16_f32 v161, v185, v187
	ds_read2_b32 v[174:175], v169 offset0:16 offset1:24
	ds_read2_b32 v[176:177], v169 offset0:81 offset1:89
	ds_read2_b32 v[178:179], v169 offset0:146 offset1:154
	ds_read2_b32 v[180:181], v169 offset0:211 offset1:219
	ds_read2_b32 v[182:183], v173 offset0:20 offset1:28
	ds_read2_b32 v[184:185], v173 offset0:85 offset1:93
	ds_read2_b32 v[186:187], v173 offset0:150 offset1:158
	ds_read2_b32 v[190:191], v173 offset0:215 offset1:223
	v_mad_u64_u32 v[4:5], s[8:9], s28, v140, 0
	v_lshl_add_u64 v[4:5], v[4:5], 1, v[188:189]
	global_store_dwordx4 v[4:5], v[158:161], off
	v_mad_u64_u32 v[4:5], s[8:9], s28, v142, 0
	s_waitcnt lgkmcnt(6)
	v_cvt_pk_bf16_f32 v158, v174, v176
	s_waitcnt lgkmcnt(4)
	v_cvt_pk_bf16_f32 v159, v178, v180
	s_waitcnt lgkmcnt(2)
	v_cvt_pk_bf16_f32 v160, v182, v184
	s_waitcnt lgkmcnt(0)
	v_cvt_pk_bf16_f32 v161, v186, v190
	v_lshl_add_u64 v[4:5], v[4:5], 1, v[188:189]
	global_store_dwordx4 v[4:5], v[158:161], off
	v_mad_u64_u32 v[4:5], s[8:9], s28, v144, 0
	s_nop 0
	v_cvt_pk_bf16_f32 v158, v175, v177
	v_cvt_pk_bf16_f32 v159, v179, v181
	v_cvt_pk_bf16_f32 v160, v183, v185
	v_cvt_pk_bf16_f32 v161, v187, v191
	ds_read2_b32 v[174:175], v169 offset0:32 offset1:40
	ds_read2_b32 v[176:177], v169 offset0:97 offset1:105
	ds_read2_b32 v[178:179], v169 offset0:162 offset1:170
	ds_read2_b32 v[180:181], v169 offset0:227 offset1:235
	ds_read2_b32 v[182:183], v173 offset0:36 offset1:44
	ds_read2_b32 v[184:185], v173 offset0:101 offset1:109
	ds_read2_b32 v[186:187], v173 offset0:166 offset1:174
	ds_read2_b32 v[190:191], v173 offset0:231 offset1:239
	v_lshl_add_u64 v[4:5], v[4:5], 1, v[188:189]
	global_store_dwordx4 v[4:5], v[158:161], off
	v_mad_u64_u32 v[4:5], s[8:9], s28, v146, 0
	s_waitcnt lgkmcnt(6)
	v_cvt_pk_bf16_f32 v158, v174, v176
	s_waitcnt lgkmcnt(4)
	v_cvt_pk_bf16_f32 v159, v178, v180
	s_waitcnt lgkmcnt(2)
	v_cvt_pk_bf16_f32 v160, v182, v184
	s_waitcnt lgkmcnt(0)
	v_cvt_pk_bf16_f32 v161, v186, v190
	v_lshl_add_u64 v[4:5], v[4:5], 1, v[188:189]
	global_store_dwordx4 v[4:5], v[158:161], off
	v_mad_u64_u32 v[4:5], s[8:9], s28, v148, 0
	s_nop 0
	v_cvt_pk_bf16_f32 v158, v175, v177
	v_cvt_pk_bf16_f32 v159, v179, v181
	v_cvt_pk_bf16_f32 v160, v183, v185
	v_cvt_pk_bf16_f32 v161, v187, v191
	ds_read2_b32 v[174:175], v169 offset0:48 offset1:56
	ds_read2_b32 v[176:177], v169 offset0:113 offset1:121
	ds_read2_b32 v[178:179], v169 offset0:178 offset1:186
	ds_read2_b32 v[180:181], v169 offset0:243 offset1:251
	ds_read2_b32 v[182:183], v173 offset0:52 offset1:60
	ds_read2_b32 v[184:185], v173 offset0:117 offset1:125
	ds_read2_b32 v[186:187], v173 offset0:182 offset1:190
	ds_read2_b32 v[190:191], v173 offset0:247 offset1:255
	v_lshl_add_u64 v[4:5], v[4:5], 1, v[188:189]
	global_store_dwordx4 v[4:5], v[158:161], off
	v_mad_u64_u32 v[4:5], s[8:9], s28, v150, 0
	s_waitcnt lgkmcnt(6)
	v_cvt_pk_bf16_f32 v158, v174, v176
	s_waitcnt lgkmcnt(4)
	v_cvt_pk_bf16_f32 v159, v178, v180
	s_waitcnt lgkmcnt(2)
	v_cvt_pk_bf16_f32 v160, v182, v184
	s_waitcnt lgkmcnt(0)
	v_cvt_pk_bf16_f32 v161, v186, v190
	v_lshl_add_u64 v[4:5], v[4:5], 1, v[188:189]
	global_store_dwordx4 v[4:5], v[158:161], off
	v_mad_u64_u32 v[4:5], s[8:9], s28, v152, 0
	s_nop 0
	v_cvt_pk_bf16_f32 v158, v175, v177
	v_cvt_pk_bf16_f32 v159, v179, v181
	v_cvt_pk_bf16_f32 v160, v183, v185
	v_cvt_pk_bf16_f32 v161, v187, v191
	v_lshl_add_u64 v[4:5], v[4:5], 1, v[188:189]
	global_store_dwordx4 v[4:5], v[158:161], off
	s_waitcnt lgkmcnt(0)

; #define GAS __attribute__((address_space(1)))
; #define LAS __attribute__((address_space(3)))
; #define LDS_WAIT() asm volatile("s_waitcnt lgkmcnt(0)" ::: "memory")
; __device__ __forceinline__ unsigned pk2(float lo, float hi) { pkf32x2 v = {lo, hi}; pkbf16x2 b = __builtin_convertvector(v, pkbf16x2); return __builtin_bit_cast(unsigned, b); }
; template <bool NT> __device__ __forceinline__ void tr_store(const f32x4 (&v)[16], const TrItem& it, LAS float* scr, int lane) {
;     const int kq = lane >> 4, g = lane & 15;
; #pragma unroll
;     for (int i = 0; i < 16; ++i) { LAS float* d = scr + (4 * i + kq) * 65 + 4 * g; d[0] = v[i].x; d[1] = v[i].y; d[2] = v[i].z; d[3] = v[i].w; }
;     LDS_WAIT(); asm volatile("" ::: "memory");
;     const int c = lane >> 3, rr = lane & 7;
; #pragma unroll
;     for (int j = 0; j < 8; ++j) { const int n = 8 * j + rr; const LAS float* s = scr + (8 * c) * 65 + n;
;         v4u o; o.x = pk2(s[0 * 65], s[1 * 65]); o.y = pk2(s[2 * 65], s[3 * 65]); o.z = pk2(s[4 * 65], s[5 * 65]); o.w = pk2(s[6 * 65], s[7 * 65]);
;         GAS v4u* q = (GAS v4u*)(it.dst + (size_t)n * it.K + 8 * c); if (NT) __builtin_nontemporal_store(o, q); else *q = o; }
;     LDS_WAIT(); asm volatile("" ::: "memory");
; }
; template <bool NT> __device__ __forceinline__ void p0_weights(Frame& F, int lo, int NITEMS, int widx, int nworkers) {
;     ...
;     for (;;) {
;         const bool hb = it + NGW < NITEMS;
;         if (hb) { tb = p0_item(F, it + NGW, g4); tr_load<NT>(vb, tb, F.lane); }
;         tr_store<NT>(va, ta, scr, F.lane);
;         if (!hb) break;
;         const bool ha = it + 2 * NGW < NITEMS;
;         if (ha) { ta = p0_item(F, it + 2 * NGW, g4); tr_load<NT>(va, ta, F.lane); }
;         tr_store<NT>(vb, tb, scr, F.lane);
;         if (!ha) break;
;         it += 2 * NGW;
;     }
.LBB0_1350:
	v_add_u32_e32 v174, 0x410, v172
	v_add_u32_e32 v175, 0x418, v172
	v_add_u32_e32 v176, 0x820, v172
	v_add_u32_e32 v177, 0x828, v172
	v_add_u32_e32 v178, 0xc30, v172
	v_add_u32_e32 v179, 0xc38, v172
	v_add_u32_e32 v180, 0x1040, v172
	v_add_u32_e32 v181, 0x1048, v172
	v_add_u32_e32 v182, 0x1450, v172
	v_add_u32_e32 v183, 0x1458, v172
	v_add_u32_e32 v184, 0x1860, v172
	v_add_u32_e32 v185, 0x1868, v172
	v_add_u32_e32 v186, 0x1c70, v172
	v_add_u32_e32 v187, 0x1c78, v172
	v_add_u32_e32 v188, 0x2080, v172
	v_add_u32_e32 v189, 0x2088, v172
	v_add_u32_e32 v190, 0x2490, v172
	v_add_u32_e32 v191, 0x2498, v172
	v_add_u32_e32 v192, 0x28a0, v172
	v_add_u32_e32 v193, 0x28a8, v172
	v_add_u32_e32 v194, 0x2cb0, v172
	v_add_u32_e32 v195, 0x2cb8, v172
	v_add_u32_e32 v196, 0x30c0, v172
	v_add_u32_e32 v197, 0x30c8, v172
	v_add_u32_e32 v198, 0x34d0, v172
	v_add_u32_e32 v199, 0x34d8, v172
	v_add_u32_e32 v200, 0x38e0, v172
	v_add_u32_e32 v201, 0x38e8, v172
	v_add_u32_e32 v202, 0x3cf0, v172
	v_add_u32_e32 v203, 0x3cf8, v172
	s_waitcnt vmcnt(0)
	ds_write2_b32 v172, v10, v11 offset1:1
	ds_write2_b32 v172, v12, v13 offset0:2 offset1:3
	ds_write2_b32 v174, v6, v7 offset1:1
	ds_write2_b32 v175, v8, v9 offset1:1
	ds_write2_b32 v176, v14, v15 offset1:1
	ds_write2_b32 v177, v16, v17 offset1:1
	ds_write2_b32 v178, v18, v19 offset1:1
	ds_write2_b32 v179, v20, v21 offset1:1
	ds_write2_b32 v180, v22, v23 offset1:1
	ds_write2_b32 v181, v24, v25 offset1:1
	ds_write2_b32 v182, v26, v27 offset1:1
	ds_write2_b32 v183, v28, v29 offset1:1
	ds_write2_b32 v184, v30, v31 offset1:1
	ds_write2_b32 v185, v32, v33 offset1:1
	ds_write2_b32 v186, v34, v35 offset1:1
	ds_write2_b32 v187, v36, v37 offset1:1
	ds_write2_b32 v188, v38, v39 offset1:1
	ds_write2_b32 v189, v40, v41 offset1:1
	ds_write2_b32 v190, v42, v43 offset1:1
	ds_write2_b32 v191, v44, v45 offset1:1
	ds_write2_b32 v192, v46, v47 offset1:1
	ds_write2_b32 v193, v48, v49 offset1:1
	ds_write2_b32 v194, v50, v51 offset1:1
	ds_write2_b32 v195, v52, v53 offset1:1
	ds_write2_b32 v196, v62, v63 offset1:1
	ds_write2_b32 v197, v64, v65 offset1:1
	ds_write2_b32 v198, v74, v75 offset1:1
	ds_write2_b32 v199, v76, v77 offset1:1
	ds_write2_b32 v200, v86, v87 offset1:1
	ds_write2_b32 v201, v88, v89 offset1:1
	ds_write2_b32 v202, v90, v91 offset1:1
	ds_write2_b32 v203, v92, v93 offset1:1
	s_waitcnt lgkmcnt(0)
	v_add_u32_e32 v173, 0x400, v169
	ds_read2_b32 v[4:5], v169 offset0:65 offset1:73
	ds_read2_b32 v[160:161], v169 offset1:8
	ds_read2_b32 v[208:209], v169 offset0:130 offset1:138
	ds_read2_b32 v[210:211], v169 offset0:195 offset1:203
	ds_read2_b32 v[212:213], v173 offset0:4 offset1:12
	ds_read2_b32 v[214:215], v173 offset0:69 offset1:77
	ds_read2_b32 v[216:217], v173 offset0:134 offset1:142
	ds_read2_b32 v[218:219], v173 offset0:199 offset1:207
	v_lshlrev_b32_e32 v158, 1, v138
	v_mov_b32_e32 v159, v2
	v_lshl_add_u64 v[220:221], v[154:155], 0, v[158:159]
	v_mad_u64_u32 v[222:223], s[8:9], s22, v136, 0
	s_waitcnt lgkmcnt(6)
	v_cvt_pk_bf16_f32 v204, v160, v4
	s_waitcnt lgkmcnt(4)
	v_cvt_pk_bf16_f32 v205, v208, v210
	s_waitcnt lgkmcnt(2)
	v_cvt_pk_bf16_f32 v206, v212, v214
	s_waitcnt lgkmcnt(0)
	v_cvt_pk_bf16_f32 v207, v216, v218
	v_lshl_add_u64 v[222:223], v[222:223], 1, v[220:221]
	global_store_dwordx4 v[222:223], v[204:207], off
	s_andn2_b64 vcc, exec, s[6:7]
	s_mov_b64 s[6:7], 0
	v_cvt_pk_bf16_f32 v204, v161, v5
	v_cvt_pk_bf16_f32 v205, v209, v211
	v_cvt_pk_bf16_f32 v206, v213, v215
	v_cvt_pk_bf16_f32 v207, v217, v219
	ds_read2_b32 v[160:161], v169 offset0:16 offset1:24
	ds_read2_b32 v[208:209], v169 offset0:81 offset1:89
	ds_read2_b32 v[210:211], v169 offset0:146 offset1:154
	ds_read2_b32 v[212:213], v169 offset0:211 offset1:219
	ds_read2_b32 v[214:215], v173 offset0:20 offset1:28
	ds_read2_b32 v[216:217], v173 offset0:85 offset1:93
	ds_read2_b32 v[218:219], v173 offset0:150 offset1:158
	ds_read2_b32 v[222:223], v173 offset0:215 offset1:223
	v_mad_u64_u32 v[4:5], s[8:9], s22, v140, 0
	v_lshl_add_u64 v[4:5], v[4:5], 1, v[220:221]
	global_store_dwordx4 v[4:5], v[204:207], off
	v_mad_u64_u32 v[4:5], s[8:9], s22, v142, 0
	s_waitcnt lgkmcnt(6)
	v_cvt_pk_bf16_f32 v204, v160, v208
	s_waitcnt lgkmcnt(4)
	v_cvt_pk_bf16_f32 v205, v210, v212
	s_waitcnt lgkmcnt(2)
	v_cvt_pk_bf16_f32 v206, v214, v216
	s_waitcnt lgkmcnt(0)
	v_cvt_pk_bf16_f32 v207, v218, v222
	v_lshl_add_u64 v[4:5], v[4:5], 1, v[220:221]
	global_store_dwordx4 v[4:5], v[204:207], off
	v_mad_u64_u32 v[4:5], s[8:9], s22, v144, 0
	s_nop 0
	v_cvt_pk_bf16_f32 v204, v161, v209
	v_cvt_pk_bf16_f32 v205, v211, v213
	v_cvt_pk_bf16_f32 v206, v215, v217
	v_cvt_pk_bf16_f32 v207, v219, v223
	ds_read2_b32 v[160:161], v169 offset0:32 offset1:40
	ds_read2_b32 v[208:209], v169 offset0:97 offset1:105
	ds_read2_b32 v[210:211], v169 offset0:162 offset1:170
	ds_read2_b32 v[212:213], v169 offset0:227 offset1:235
	ds_read2_b32 v[214:215], v173 offset0:36 offset1:44
	ds_read2_b32 v[216:217], v173 offset0:101 offset1:109
	ds_read2_b32 v[218:219], v173 offset0:166 offset1:174
	ds_read2_b32 v[222:223], v173 offset0:231 offset1:239
	v_lshl_add_u64 v[4:5], v[4:5], 1, v[220:221]
	global_store_dwordx4 v[4:5], v[204:207], off
	v_mad_u64_u32 v[4:5], s[8:9], s22, v146, 0
	s_waitcnt lgkmcnt(6)
	v_cvt_pk_bf16_f32 v204, v160, v208
	s_waitcnt lgkmcnt(4)
	v_cvt_pk_bf16_f32 v205, v210, v212
	s_waitcnt lgkmcnt(2)
	v_cvt_pk_bf16_f32 v206, v214, v216
	s_waitcnt lgkmcnt(0)
	v_cvt_pk_bf16_f32 v207, v218, v222
	v_lshl_add_u64 v[4:5], v[4:5], 1, v[220:221]
	global_store_dwordx4 v[4:5], v[204:207], off
	v_mad_u64_u32 v[4:5], s[8:9], s22, v148, 0
	s_nop 0
	v_cvt_pk_bf16_f32 v204, v161, v209
	v_cvt_pk_bf16_f32 v205, v211, v213
	v_cvt_pk_bf16_f32 v206, v215, v217
	v_cvt_pk_bf16_f32 v207, v219, v223
	ds_read2_b32 v[160:161], v169 offset0:48 offset1:56
	ds_read2_b32 v[208:209], v169 offset0:113 offset1:121
	ds_read2_b32 v[210:211], v169 offset0:178 offset1:186
	ds_read2_b32 v[212:213], v169 offset0:243 offset1:251
	ds_read2_b32 v[214:215], v173 offset0:52 offset1:60
	ds_read2_b32 v[216:217], v173 offset0:117 offset1:125
	ds_read2_b32 v[218:219], v173 offset0:182 offset1:190
	ds_read2_b32 v[222:223], v173 offset0:247 offset1:255
	v_lshl_add_u64 v[4:5], v[4:5], 1, v[220:221]
	global_store_dwordx4 v[4:5], v[204:207], off
	v_mad_u64_u32 v[4:5], s[8:9], s22, v150, 0
	s_waitcnt lgkmcnt(6)
	v_cvt_pk_bf16_f32 v204, v160, v208
	s_waitcnt lgkmcnt(4)
	v_cvt_pk_bf16_f32 v205, v210, v212
	s_waitcnt lgkmcnt(2)
	v_cvt_pk_bf16_f32 v206, v214, v216
	s_waitcnt lgkmcnt(0)
	v_cvt_pk_bf16_f32 v207, v218, v222
	v_lshl_add_u64 v[4:5], v[4:5], 1, v[220:221]
	global_store_dwordx4 v[4:5], v[204:207], off
	v_mad_u64_u32 v[4:5], s[8:9], s22, v152, 0
	s_nop 0
	v_cvt_pk_bf16_f32 v204, v161, v209
	v_cvt_pk_bf16_f32 v205, v211, v213
	v_cvt_pk_bf16_f32 v206, v215, v217
	v_cvt_pk_bf16_f32 v207, v219, v223
	v_lshl_add_u64 v[4:5], v[4:5], 1, v[220:221]
	global_store_dwordx4 v[4:5], v[204:207], off
	s_waitcnt lgkmcnt(0)
	s_cbranch_vccnz .LBB0_1289
; __device__ __forceinline__ TrItem p0_item(Frame& F, int it, int g4) {
;     constexpr int I_IN = (DM / 64) * (NPT / 64), I_OUT = (DM / 64) * (DM / 64), I_GU = (DM / 64) * (2 * FF / 64);
;     bf16* win_t = (bf16*)(F.ws + WS_WIN); bf16* wout_t = (bf16*)(F.ws + WS_WOUT); bf16* wgu_t = (bf16*)(F.ws + WS_WGU); bf16* wd_t = (bf16*)(F.ws + WS_WD);
;     TrItem t; int r = it;
;     if (r < I_IN) { const int kb = r % (DM / 64), nb = r / (DM / 64); const int sc = win_srccol(nb * 64 + g4);
;         t.colp = sc >= 0 ? F.w_in + (size_t)(kb * 64) * IN_COLS + sc : nullptr; t.ldw = IN_COLS; t.K = LDWIN; t.dst = win_t + (size_t)(nb * 64) * LDWIN + kb * 64; return t; } r -= I_IN;
;     if (r < I_OUT) { const int kb = r % (DM / 64), nb = r / (DM / 64);
;         t.colp = F.w_out + (size_t)(kb * 64) * DM + nb * 64 + g4; t.ldw = DM; t.K = LDWOUT; t.dst = wout_t + (size_t)(nb * 64) * LDWOUT + kb * 64; return t; } r -= I_OUT;
;     if (r < I_GU) { const int kb = r % (DM / 64), nb = r / (DM / 64); const int n = nb * 64 + g4;
;         const float* src = ((n >> 7) & 1) ? F.w_up : F.w_gate;
;         t.colp = src + (size_t)(kb * 64) * FF + (n >> 8) * 128 + (n & 127); t.ldw = FF; t.K = LDWGU; t.dst = wgu_t + (size_t)(nb * 64) * LDWGU + kb * 64; return t; } r -= I_GU;
;     { const int kb = r % (FF / 64), nb = r / (FF / 64);
;         t.colp = F.w_down + (size_t)(kb * 64) * DM + nb * 64 + g4; t.ldw = DM; t.K = FF; t.dst = wd_t + (size_t)(nb * 64) * FF + kb * 64; return t; }
; }
; template <bool NT> __device__ __forceinline__ void p0_weights(Frame& F, int lo, int NITEMS, int widx, int nworkers) {
;     ...
;         const bool ha = it + 2 * NGW < NITEMS;
;         if (ha) { ta = p0_item(F, it + 2 * NGW, g4); tr_load<NT>(va, ta, F.lane); }
	s_cmp_lt_i32 s27, 0xa500
	s_cselect_b64 s[6:7], -1, 0
	s_cmp_gt_i32 s27, 0xa4ff
	s_cbranch_scc1 .LBB0_1356
	s_add_i32 s29, s27, 0x400
	s_cmpk_gt_i32 s27, 0x343f
	s_cbranch_scc0 .LBB0_1357
	s_cmpk_gt_u32 s29, 0x483f
	s_cbranch_scc0 .LBB0_1360
	s_cmpk_gt_u32 s29, 0x9e3f
	s_cbranch_scc0 .LBB0_1361
	s_add_i32 s4, s29, 0x61c0
	s_and_b32 s8, s4, 0xffff
	s_mul_i32 s8, s8, 0xbe83
	s_lshr_b32 s8, s8, 23
	s_mul_i32 s9, s8, 0xac
	s_sub_i32 s4, s4, s9
	s_lshl_b32 s4, s4, 6
	s_and_b32 s4, s4, 0xffc0
	s_lshl_b32 s9, s4, 14
	s_add_u32 s9, s78, s9
	s_addc_u32 s10, s79, 0
	s_lshl_b32 s11, s8, 6
	s_lshl_b32 s8, s8, 8
	s_add_u32 s8, s9, s8
	s_addc_u32 s9, s10, 0
	v_lshlrev_b32_e32 v4, 2, v134
	v_mov_b32_e32 v5, v2
	v_lshl_add_u64 v[160:161], s[8:9], 0, v[4:5]
	v_mov_b64_e32 v[4:5], s[0:1]
	v_mad_u64_u32 v[4:5], s[8:9], s11, v170, v[4:5]
	s_lshl_b32 s4, s4, 1
	v_lshl_add_u64 v[154:155], v[4:5], 0, s[4:5]
	s_mov_b64 s[8:9], 0
	s_branch .LBB0_1362
